# adaLN K loops: the 9 A-fragment LDS reads of a K-step issued together into extra registers (no read-wait-MFMA rounds) on top of k3
# baseline (speedup 1.0000x reference)
; __device__ __forceinline__ unsigned cvt_pk_bf16(float lo, float hi) { unsigned r; asm volatile("v_cvt_pk_bf16_f32 %0, %1, %2" : "=v"(r) : "v"(lo), "v"(hi)); return r; }
; #define LAS __attribute__((address_space(3)))
; #define MODI_LOAD(b, s) do { _Pragma("unroll") for (int i = 0; i < 4; ++i) buf[b][i] = __builtin_nontemporal_load((const GAS f32x4*)(Wb + (size_t)(32 * (s) + 16 * (i >> 1) + (i & 1)) * (MODW * 4) + wlo)); } while (0)
; #define MODI_ALOAD(r, s) do { const int s_ = (s) < nsteps ? (s) : nsteps - 1; ar[r][0] = *(const GAS v4u*)(Cb + (size_t)s_ * 9216 + c1); ar[r][1] = *(const GAS v4u*)(Cb + (size_t)s_ * 9216 + c2); } while (0)
; __device__ __forceinline__ void mod_item256(Frame& F, const Args& A, int cg, int k0, int nsteps, float* dst, int ldd, int dcol0, const float* bias) {
;     ...
;     for (int s4 = 0; s4 < nsteps; s4 += 2) {
; #pragma unroll
;         for (int b = 0; b < 2; ++b) { const int s = s4 + b;
; #pragma unroll
;             for (int ip = 0; ip < 2; ++ip)
; #pragma unroll
;                 for (int e = 0; e < 4; ++e) { const int n = n4 + e, k = 2 * kp + 16 * ip;
;                     *(LAS unsigned*)(sb + n * 80 + (((k >> 3) ^ (a8 & 3)) * 16) + (k & 7) * 2) = pg8::cvt_pk_bf16(buf[b][2 * ip][e], buf[b][2 * ip + 1][e]); }
;             asm volatile("" ::: "memory");
;             { const int sn = (s + 2 < nsteps) ? s + 2 : nsteps - 1; MODI_LOAD(b, sn); }
;             asm volatile("" ::: "memory");
;             bf16x8 bfr[2];
; #pragma unroll
;             for (int j = 0; j < 2; ++j) { const int n = 16 * j + (lane & 15); bfr[j] = *(const LAS bf16x8*)(sb + n * 80 + (((lane >> 4) ^ ((n >> 2) & 3)) * 16)); }
; #pragma unroll
;             for (int mg = 0; mg < 3; ++mg) { bf16x8 af[3];
; #pragma unroll
;                 for (int i = 0; i < 3; ++i) af[i] = *(const LAS bf16x8*)(la + (s & 1) * MODI_A_BYTES + (3 * mg + i) * 1024 + lane * 16);
; #pragma unroll
;                 for (int i = 0; i < 3; ++i)
; #pragma unroll
;                     for (int j = 0; j < 2; ++j) acc[3 * mg + i][j] = __builtin_amdgcn_mfma_f32_16x16x32_bf16(af[i], bfr[j], acc[3 * mg + i][j], 0, 0, 0);
;                 asm volatile("" ::: "memory"); }
;             MODI_AWRITE((b + 1) & 1, s + 1);
;             asm volatile("" ::: "memory");
;             MODI_ALOAD((b + 1) & 1, s + 3);
;             __syncthreads();
;         }
.LBB0_81:
	s_waitcnt vmcnt(10)
	v_cvt_pk_bf16_f32 v2, v2, v14
	ds_write_b32 v165, v2
	v_cvt_pk_bf16_f32 v2, v3, v15
	ds_write_b32 v165, v2 offset:80
	v_cvt_pk_bf16_f32 v2, v4, v16
	ds_write_b32 v165, v2 offset:160
	v_cvt_pk_bf16_f32 v2, v5, v17
	s_add_i32 s18, s19, 2
	ds_write_b32 v165, v2 offset:240
	s_waitcnt vmcnt(8)
	v_cvt_pk_bf16_f32 v2, v6, v10
	ds_write_b32 v166, v2
	v_cvt_pk_bf16_f32 v2, v7, v11
	s_min_u32 s6, s18, 29
	ds_write_b32 v166, v2 offset:80
	v_cvt_pk_bf16_f32 v2, v8, v12
	s_mul_i32 s6, s6, 0x480000
	ds_write_b32 v166, v2 offset:160
	v_cvt_pk_bf16_f32 v2, v9, v13
	v_lshl_add_u64 v[10:11], v[160:161], 0, s[6:7]
	ds_write_b32 v166, v2 offset:240
	v_add_co_u32_e32 v2, vcc, s59, v10
	s_min_u32 s6, s18, 28
	s_nop 0
	v_addc_co_u32_e32 v3, vcc, 0, v11, vcc
	v_add_co_u32_e32 v6, vcc, s70, v10
	global_load_dwordx4 v[2:5], v[2:3], off nt
	s_nop 0
	v_addc_co_u32_e32 v7, vcc, 0, v11, vcc
	global_load_dwordx4 v[14:17], v[6:7], off nt
	v_add_co_u32_e32 v6, vcc, s71, v10
	s_mulk_i32 s6, 0x2400
	s_nop 0
	v_addc_co_u32_e32 v7, vcc, 0, v11, vcc
	v_add_co_u32_e32 v10, vcc, s72, v10
	global_load_dwordx4 v[6:9], v[6:7], off nt
	s_nop 0
	v_addc_co_u32_e32 v11, vcc, 0, v11, vcc
	global_load_dwordx4 v[10:13], v[10:11], off nt
	ds_read_b128 v[172:175], v167
	ds_read_b128 v[176:179], v167 offset:1280
	ds_read_b128 v[180:183], v168 offset:20480
	ds_read_b128 v[184:187], v168 offset:21504
	ds_read_b128 v[188:191], v168 offset:22528
	ds_read_b128 v[196:199], v168 offset:23552
	ds_read_b128 v[200:203], v168 offset:24576
	ds_read_b128 v[204:207], v168 offset:25600
	ds_read_b128 v[208:211], v168 offset:26624
	ds_read_b128 v[212:215], v168 offset:27648
	ds_read_b128 v[216:219], v168 offset:28672
	s_waitcnt lgkmcnt(8)
	v_mfma_f32_16x16x32_bf16 v[118:121], v[180:183], v[172:175], v[118:121]
	s_add_u32 s6, s16, s6
	s_addc_u32 s21, s17, 0
	s_add_u32 s20, s6, 0x6c00
	v_mfma_f32_16x16x32_bf16 v[90:93], v[180:183], v[176:179], v[90:93]
	s_addc_u32 s21, s21, 0
	s_add_i32 s19, s19, 3
	s_min_u32 s6, s19, 29
	s_waitcnt lgkmcnt(7)
	v_mfma_f32_16x16x32_bf16 v[114:117], v[184:187], v[172:175], v[114:117]
	s_mul_i32 s6, s6, 0x480000
	v_mfma_f32_16x16x32_bf16 v[78:81], v[184:187], v[176:179], v[78:81]
	s_waitcnt lgkmcnt(6)
	v_mfma_f32_16x16x32_bf16 v[110:113], v[188:191], v[172:175], v[110:113]
	v_mfma_f32_16x16x32_bf16 v[74:77], v[188:191], v[176:179], v[74:77]
	s_waitcnt lgkmcnt(5)
	v_mfma_f32_16x16x32_bf16 v[106:109], v[196:199], v[172:175], v[106:109]
	v_mfma_f32_16x16x32_bf16 v[70:73], v[196:199], v[176:179], v[70:73]
	s_waitcnt lgkmcnt(4)
	v_mfma_f32_16x16x32_bf16 v[102:105], v[200:203], v[172:175], v[102:105]
	v_mfma_f32_16x16x32_bf16 v[66:69], v[200:203], v[176:179], v[66:69]
	s_waitcnt lgkmcnt(3)
	v_mfma_f32_16x16x32_bf16 v[98:101], v[204:207], v[172:175], v[98:101]
	v_mfma_f32_16x16x32_bf16 v[62:65], v[204:207], v[176:179], v[62:65]
	s_waitcnt vmcnt(7)
	ds_write_b128 v169, v[38:41] offset:29696
	s_waitcnt vmcnt(6)
	ds_write_b128 v170, v[42:45] offset:37888
	v_lshl_add_u64 v[38:39], s[20:21], 0, v[124:125]
	v_lshl_add_u64 v[42:43], s[20:21], 0, v[126:127]
	global_load_dwordx4 v[38:41], v[38:39], off
	s_waitcnt lgkmcnt(4)
	v_mfma_f32_16x16x32_bf16 v[94:97], v[208:211], v[172:175], v[94:97]
	global_load_dwordx4 v[42:45], v[42:43], off
	s_waitcnt lgkmcnt(0)
	s_barrier
	v_cvt_pk_bf16_f32 v26, v26, v30
	ds_write_b32 v165, v26
	v_cvt_pk_bf16_f32 v26, v27, v31
	ds_write_b32 v165, v26 offset:80
	v_cvt_pk_bf16_f32 v26, v28, v32
	ds_write_b32 v165, v26 offset:160
	v_cvt_pk_bf16_f32 v26, v29, v33
	ds_write_b32 v165, v26 offset:240
	v_cvt_pk_bf16_f32 v26, v34, v50
	ds_write_b32 v166, v26
	v_cvt_pk_bf16_f32 v26, v35, v51
	ds_write_b32 v166, v26 offset:80
	v_cvt_pk_bf16_f32 v26, v36, v52
	ds_write_b32 v166, v26 offset:160
	v_cvt_pk_bf16_f32 v26, v37, v53
	v_lshl_add_u64 v[50:51], v[160:161], 0, s[6:7]
	ds_write_b32 v166, v26 offset:240
	v_add_co_u32_e32 v26, vcc, s59, v50
	v_mfma_f32_16x16x32_bf16 v[58:61], v[208:211], v[176:179], v[58:61]
	s_nop 0
	v_addc_co_u32_e32 v27, vcc, 0, v51, vcc
	v_add_co_u32_e32 v30, vcc, s70, v50
	global_load_dwordx4 v[26:29], v[26:27], off nt
	s_nop 0
	v_addc_co_u32_e32 v31, vcc, 0, v51, vcc
	v_add_co_u32_e32 v34, vcc, s71, v50
	global_load_dwordx4 v[30:33], v[30:31], off nt
	s_nop 0
	v_addc_co_u32_e32 v35, vcc, 0, v51, vcc
	v_add_co_u32_e32 v50, vcc, s72, v50
	global_load_dwordx4 v[34:37], v[34:35], off nt
	s_nop 0
	v_addc_co_u32_e32 v51, vcc, 0, v51, vcc
	global_load_dwordx4 v[50:53], v[50:51], off nt
	v_mfma_f32_16x16x32_bf16 v[86:89], v[212:215], v[172:175], v[86:89]
	s_min_u32 s6, s19, 28
	s_mulk_i32 s6, 0x2400
	s_add_u32 s6, s16, s6
	v_mfma_f32_16x16x32_bf16 v[54:57], v[212:215], v[176:179], v[54:57]
	s_addc_u32 s19, s17, 0
	s_add_u32 s20, s6, 0x6c00
	s_addc_u32 s21, s19, 0
	v_mfma_f32_16x16x32_bf16 v[82:85], v[216:219], v[172:175], v[82:85]
	s_cmp_lt_u32 s18, 30
	s_mov_b32 s19, s18
	v_mfma_f32_16x16x32_bf16 v[46:49], v[216:219], v[176:179], v[46:49]
	ds_read_b128 v[172:175], v167
	ds_read_b128 v[176:179], v167 offset:1280
	ds_read_b128 v[180:183], v168 offset:29696
	ds_read_b128 v[184:187], v168 offset:30720
	ds_read_b128 v[188:191], v168 offset:31744
	ds_read_b128 v[196:199], v168 offset:32768
	ds_read_b128 v[200:203], v168 offset:33792
	ds_read_b128 v[204:207], v168 offset:34816
	ds_read_b128 v[208:211], v168 offset:35840
	ds_read_b128 v[212:215], v168 offset:36864
	ds_read_b128 v[216:219], v168 offset:37888
	s_waitcnt lgkmcnt(8)
	v_mfma_f32_16x16x32_bf16 v[118:121], v[180:183], v[172:175], v[118:121]
	v_mfma_f32_16x16x32_bf16 v[90:93], v[180:183], v[176:179], v[90:93]
	s_waitcnt lgkmcnt(7)
	v_mfma_f32_16x16x32_bf16 v[114:117], v[184:187], v[172:175], v[114:117]
	v_mfma_f32_16x16x32_bf16 v[78:81], v[184:187], v[176:179], v[78:81]
	s_waitcnt lgkmcnt(6)
	v_mfma_f32_16x16x32_bf16 v[110:113], v[188:191], v[172:175], v[110:113]
	v_mfma_f32_16x16x32_bf16 v[74:77], v[188:191], v[176:179], v[74:77]
	s_waitcnt lgkmcnt(5)
	v_mfma_f32_16x16x32_bf16 v[106:109], v[196:199], v[172:175], v[106:109]
	v_mfma_f32_16x16x32_bf16 v[70:73], v[196:199], v[176:179], v[70:73]
	s_waitcnt lgkmcnt(4)
	v_mfma_f32_16x16x32_bf16 v[102:105], v[200:203], v[172:175], v[102:105]
	v_mfma_f32_16x16x32_bf16 v[66:69], v[200:203], v[176:179], v[66:69]
	s_waitcnt lgkmcnt(3)
	v_mfma_f32_16x16x32_bf16 v[98:101], v[204:207], v[172:175], v[98:101]
	v_mfma_f32_16x16x32_bf16 v[62:65], v[204:207], v[176:179], v[62:65]
	s_waitcnt vmcnt(11)
	ds_write_b128 v169, v[18:21] offset:20480
	s_waitcnt vmcnt(10)
	ds_write_b128 v170, v[22:25] offset:28672
	v_lshl_add_u64 v[18:19], s[20:21], 0, v[124:125]
	v_lshl_add_u64 v[22:23], s[20:21], 0, v[126:127]
	global_load_dwordx4 v[18:21], v[18:19], off
	s_waitcnt lgkmcnt(4)
	v_mfma_f32_16x16x32_bf16 v[94:97], v[208:211], v[172:175], v[94:97]
	global_load_dwordx4 v[22:25], v[22:23], off
	s_waitcnt lgkmcnt(0)
	s_barrier
; #define LAS __attribute__((address_space(3)))
; #define MODI_ALOAD(r, s) do { const int s_ = (s) < nsteps ? (s) : nsteps - 1; ar[r][0] = *(const GAS v4u*)(Cb + (size_t)s_ * 9216 + c1); ar[r][1] = *(const GAS v4u*)(Cb + (size_t)s_ * 9216 + c2); } while (0)
; #define MODI_AWRITE(r, s) do { *(LAS v4u*)(la + ((s) & 1) * MODI_A_BYTES + c1) = ar[r][0]; *(LAS v4u*)(la + ((s) & 1) * MODI_A_BYTES + c2) = ar[r][1]; } while (0)
; __device__ __forceinline__ void mod_item256(Frame& F, const Args& A, int cg, int k0, int nsteps, float* dst, int ldd, int dcol0, const float* bias) {
;     ...
;             for (int j = 0; j < 2; ++j) { const int n = 16 * j + (lane & 15); bfr[j] = *(const LAS bf16x8*)(sb + n * 80 + (((lane >> 4) ^ ((n >> 2) & 3)) * 16)); }
; #pragma unroll
;             for (int mg = 0; mg < 3; ++mg) { bf16x8 af[3];
; #pragma unroll
;                 for (int i = 0; i < 3; ++i) af[i] = *(const LAS bf16x8*)(la + (s & 1) * MODI_A_BYTES + (3 * mg + i) * 1024 + lane * 16);
; #pragma unroll
;                 for (int i = 0; i < 3; ++i)
; #pragma unroll
;                     for (int j = 0; j < 2; ++j) acc[3 * mg + i][j] = __builtin_amdgcn_mfma_f32_16x16x32_bf16(af[i], bfr[j], acc[3 * mg + i][j], 0, 0, 0);
;                 asm volatile("" ::: "memory"); }
;             MODI_AWRITE((b + 1) & 1, s + 1);
;             asm volatile("" ::: "memory");
;             MODI_ALOAD((b + 1) & 1, s + 3);
;             __syncthreads();
;         }
;     ...
;     const int c0 = 32 * w + (lane & 15);
; #pragma unroll
;     for (int j = 0; j < 2; ++j) { const float bv = bias ? bias[256 * cg + c0 + 16 * j] : 0.f;
; #pragma unroll
;         for (int mt = 0; mt < 9; ++mt)
; #pragma unroll
;             for (int r = 0; r < 4; ++r) { const int row = 16 * mt + 4 * (lane >> 4) + r;
;                 if (row <= DBATCH) dst[(size_t)row * ldd + dcol0 + c0 + 16 * j] = acc[mt][j][r] + bv; } }
	v_mfma_f32_16x16x32_bf16 v[58:61], v[208:211], v[176:179], v[58:61]
	v_mfma_f32_16x16x32_bf16 v[86:89], v[212:215], v[172:175], v[86:89]
	v_mfma_f32_16x16x32_bf16 v[54:57], v[212:215], v[176:179], v[54:57]
	v_mfma_f32_16x16x32_bf16 v[82:85], v[216:219], v[172:175], v[82:85]
	v_mfma_f32_16x16x32_bf16 v[46:49], v[216:219], v[176:179], v[46:49]
	s_cbranch_scc1 .LBB0_81
	s_mul_i32 s15, s15, 0x60c000
	s_add_u32 s6, s0, s15
	s_addc_u32 s18, s1, 0
	s_ashr_i32 s15, s14, 31
	s_lshl_b64 s[16:17], s[14:15], 2
	s_add_u32 s16, s6, s16
	s_addc_u32 s17, s18, s17
	s_waitcnt vmcnt(9)
	v_lshl_add_u64 v[6:7], v[128:129], 2, s[16:17]
	v_add_f32_e32 v4, 0, v118
	v_lshl_add_u64 v[2:3], v[6:7], 0, v[130:131]
	global_store_dword v[2:3], v4, off
	v_add_f32_e32 v8, 0, v119
	v_lshl_add_u64 v[4:5], v[6:7], 0, v[132:133]
	s_mov_b32 s6, 0x18000
	global_store_dword v[4:5], v8, off
	v_add_co_u32_e32 v4, vcc, s6, v2
	v_add_f32_e32 v8, 0, v120
	s_nop 0
	v_addc_co_u32_e32 v5, vcc, 0, v3, vcc
	global_store_dword v[4:5], v8, off
	v_add_f32_e32 v4, 0, v121
	s_waitcnt vmcnt(3)
	v_lshl_add_u64 v[24:25], v[6:7], 0, v[134:135]
	s_mov_b32 s6, 0xc0000
	global_store_dword v[24:25], v4, off
	v_add_co_u32_e32 v4, vcc, s6, v2
	v_add_f32_e32 v8, 0, v114
	s_nop 0
	v_addc_co_u32_e32 v5, vcc, 0, v3, vcc
	s_mov_b32 s6, 0xcc000
	global_store_dword v[4:5], v8, off
	v_add_co_u32_e32 v4, vcc, s6, v2
	v_add_f32_e32 v8, 0, v115
	s_nop 0
	v_addc_co_u32_e32 v5, vcc, 0, v3, vcc
	s_mov_b32 s6, 0xd8000
	global_store_dword v[4:5], v8, off
	v_add_co_u32_e32 v4, vcc, s6, v2
	v_add_f32_e32 v8, 0, v116
	s_nop 0
	v_addc_co_u32_e32 v5, vcc, 0, v3, vcc
	global_store_dword v[4:5], v8, off
	v_add_f32_e32 v4, 0, v117
	v_lshl_add_u64 v[22:23], v[6:7], 0, v[136:137]
	s_mov_b32 s6, 0x180000
	global_store_dword v[22:23], v4, off
	v_add_co_u32_e32 v4, vcc, s6, v2
	v_add_f32_e32 v8, 0, v110
	s_nop 0
	v_addc_co_u32_e32 v5, vcc, 0, v3, vcc
	s_mov_b32 s6, 0x18c000
	global_store_dword v[4:5], v8, off
	v_add_co_u32_e32 v4, vcc, s6, v2
	v_add_f32_e32 v8, 0, v111
	s_nop 0
	v_addc_co_u32_e32 v5, vcc, 0, v3, vcc
	s_mov_b32 s6, 0x198000
	global_store_dword v[4:5], v8, off
	v_add_co_u32_e32 v4, vcc, s6, v2
	v_add_f32_e32 v8, 0, v112
	s_nop 0
	v_addc_co_u32_e32 v5, vcc, 0, v3, vcc
	global_store_dword v[4:5], v8, off
	v_add_f32_e32 v4, 0, v113
	v_lshl_add_u64 v[18:19], v[6:7], 0, v[138:139]
	v_add_co_u32_e32 v20, vcc, s57, v2
	global_store_dword v[18:19], v4, off
	v_add_f32_e32 v4, 0, v106
	v_addc_co_u32_e32 v21, vcc, 0, v3, vcc
	s_mov_b32 s6, 0x24c000
	global_store_dword v[20:21], v4, off
	v_add_co_u32_e32 v4, vcc, s6, v2
	v_add_f32_e32 v8, 0, v107
	s_nop 0
	v_addc_co_u32_e32 v5, vcc, 0, v3, vcc
	s_mov_b32 s6, 0x258000
	global_store_dword v[4:5], v8, off
	v_add_co_u32_e32 v4, vcc, s6, v2
	v_add_f32_e32 v8, 0, v108
	s_nop 0
	v_addc_co_u32_e32 v5, vcc, 0, v3, vcc
	global_store_dword v[4:5], v8, off
	v_add_f32_e32 v4, 0, v109
	v_lshl_add_u64 v[16:17], v[6:7], 0, v[140:141]
	global_store_dword v[16:17], v4, off
	v_add_f32_e32 v8, 0, v102
	v_lshl_add_u64 v[4:5], v[6:7], 0, v[142:143]
	global_store_dword v[4:5], v8, off
	v_add_f32_e32 v8, 0, v103
	v_lshl_add_u64 v[4:5], v[6:7], 0, v[144:145]
	s_mov_b32 s6, 0x318000
	global_store_dword v[4:5], v8, off
	v_add_co_u32_e32 v4, vcc, s6, v2
	v_add_f32_e32 v8, 0, v104
	s_nop 0
	v_addc_co_u32_e32 v5, vcc, 0, v3, vcc
	global_store_dword v[4:5], v8, off
	v_add_f32_e32 v4, 0, v105
	v_lshl_add_u64 v[14:15], v[6:7], 0, v[146:147]
	s_mov_b32 s6, 0x3c0000
	global_store_dword v[14:15], v4, off
	v_add_co_u32_e32 v4, vcc, s6, v2
	v_add_f32_e32 v8, 0, v98
	s_nop 0
	v_addc_co_u32_e32 v5, vcc, 0, v3, vcc
	s_mov_b32 s6, 0x3cc000
	global_store_dword v[4:5], v8, off
	v_add_co_u32_e32 v4, vcc, s6, v2
	v_add_f32_e32 v8, 0, v99
	s_nop 0
	v_addc_co_u32_e32 v5, vcc, 0, v3, vcc
	global_store_dword v[4:5], v8, off
	v_add_co_u32_e32 v4, vcc, s73, v2
	v_add_f32_e32 v8, 0, v100
	s_nop 0
	v_addc_co_u32_e32 v5, vcc, 0, v3, vcc
	global_store_dword v[4:5], v8, off
	v_add_f32_e32 v4, 0, v101
	v_lshl_add_u64 v[10:11], v[6:7], 0, v[148:149]
	v_add_co_u32_e32 v12, vcc, s58, v2
	global_store_dword v[10:11], v4, off
	v_add_f32_e32 v4, 0, v94
	v_addc_co_u32_e32 v13, vcc, 0, v3, vcc
	global_store_dword v[12:13], v4, off
	v_add_co_u32_e32 v4, vcc, s84, v2
	v_add_f32_e32 v8, 0, v95
	s_nop 0
	v_addc_co_u32_e32 v5, vcc, 0, v3, vcc
	global_store_dword v[4:5], v8, off
	v_add_co_u32_e32 v4, vcc, s85, v2
	v_add_f32_e32 v8, 0, v96
	s_nop 0
	v_addc_co_u32_e32 v5, vcc, 0, v3, vcc
	global_store_dword v[4:5], v8, off
	v_add_f32_e32 v4, 0, v97
	v_lshl_add_u64 v[8:9], v[6:7], 0, v[150:151]
	global_store_dword v[8:9], v4, off
	v_add_co_u32_e32 v4, vcc, s86, v2
	v_add_f32_e32 v26, 0, v86
	s_nop 0
	v_addc_co_u32_e32 v5, vcc, 0, v3, vcc
	global_store_dword v[4:5], v26, off
	v_add_co_u32_e32 v4, vcc, 0x54c000, v2
	v_add_f32_e32 v26, 0, v87
	s_nop 0
	v_addc_co_u32_e32 v5, vcc, 0, v3, vcc
	global_store_dword v[4:5], v26, off
	v_add_co_u32_e32 v4, vcc, 0x558000, v2
	v_add_f32_e32 v26, 0, v88
	s_nop 0
	v_addc_co_u32_e32 v5, vcc, 0, v3, vcc
	global_store_dword v[4:5], v26, off
	v_add_f32_e32 v26, 0, v89
	v_lshl_add_u64 v[4:5], v[6:7], 0, v[152:153]
	global_store_dword v[4:5], v26, off
	s_and_saveexec_b64 s[16:17], s[2:3]
	s_cbranch_execz .LBB0_84
	v_add_f32_e32 v28, 0, v82
	v_lshl_add_u64 v[26:27], v[6:7], 0, v[154:155]
	global_store_dword v[26:27], v28, off

; __device__ __forceinline__ unsigned cvt_pk_bf16(float lo, float hi) { unsigned r; asm volatile("v_cvt_pk_bf16_f32 %0, %1, %2" : "=v"(r) : "v"(lo), "v"(hi)); return r; }
; #define LAS __attribute__((address_space(3)))
; #define MODI_LOAD(b, s) do { _Pragma("unroll") for (int i = 0; i < 4; ++i) buf[b][i] = __builtin_nontemporal_load((const GAS f32x4*)(Wb + (size_t)(32 * (s) + 16 * (i >> 1) + (i & 1)) * (MODW * 4) + wlo)); } while (0)
; #define MODI_ALOAD(r, s) do { const int s_ = (s) < nsteps ? (s) : nsteps - 1; ar[r][0] = *(const GAS v4u*)(Cb + (size_t)s_ * 9216 + c1); ar[r][1] = *(const GAS v4u*)(Cb + (size_t)s_ * 9216 + c2); } while (0)
; __device__ __forceinline__ void mod_item256(Frame& F, const Args& A, int cg, int k0, int nsteps, float* dst, int ldd, int dcol0, const float* bias) {
;     ...
;     for (int s4 = 0; s4 < nsteps; s4 += 2) {
; #pragma unroll
;         for (int b = 0; b < 2; ++b) { const int s = s4 + b;
; #pragma unroll
;             for (int ip = 0; ip < 2; ++ip)
; #pragma unroll
;                 for (int e = 0; e < 4; ++e) { const int n = n4 + e, k = 2 * kp + 16 * ip;
;                     *(LAS unsigned*)(sb + n * 80 + (((k >> 3) ^ (a8 & 3)) * 16) + (k & 7) * 2) = pg8::cvt_pk_bf16(buf[b][2 * ip][e], buf[b][2 * ip + 1][e]); }
;             asm volatile("" ::: "memory");
;             { const int sn = (s + 2 < nsteps) ? s + 2 : nsteps - 1; MODI_LOAD(b, sn); }
;             asm volatile("" ::: "memory");
;             bf16x8 bfr[2];
; #pragma unroll
;             for (int j = 0; j < 2; ++j) { const int n = 16 * j + (lane & 15); bfr[j] = *(const LAS bf16x8*)(sb + n * 80 + (((lane >> 4) ^ ((n >> 2) & 3)) * 16)); }
; #pragma unroll
;             for (int mg = 0; mg < 3; ++mg) { bf16x8 af[3];
; #pragma unroll
;                 for (int i = 0; i < 3; ++i) af[i] = *(const LAS bf16x8*)(la + (s & 1) * MODI_A_BYTES + (3 * mg + i) * 1024 + lane * 16);
; #pragma unroll
;                 for (int i = 0; i < 3; ++i)
; #pragma unroll
;                     for (int j = 0; j < 2; ++j) acc[3 * mg + i][j] = __builtin_amdgcn_mfma_f32_16x16x32_bf16(af[i], bfr[j], acc[3 * mg + i][j], 0, 0, 0);
;                 asm volatile("" ::: "memory"); }
;             MODI_AWRITE((b + 1) & 1, s + 1);
;             asm volatile("" ::: "memory");
;             MODI_ALOAD((b + 1) & 1, s + 3);
;             __syncthreads();
;         }
.LBB0_354:
	s_waitcnt vmcnt(10)
	v_cvt_pk_bf16_f32 v2, v2, v14
	ds_write_b32 v166, v2
	v_cvt_pk_bf16_f32 v2, v3, v15
	ds_write_b32 v166, v2 offset:80
	v_cvt_pk_bf16_f32 v2, v4, v16
	ds_write_b32 v166, v2 offset:160
	v_cvt_pk_bf16_f32 v2, v5, v17
	s_add_i32 s18, s19, 2
	ds_write_b32 v166, v2 offset:240
	s_waitcnt vmcnt(8)
	v_cvt_pk_bf16_f32 v2, v6, v10
	ds_write_b32 v167, v2
	v_cvt_pk_bf16_f32 v2, v7, v11
	s_min_u32 s4, s18, 29
	ds_write_b32 v167, v2 offset:80
	v_cvt_pk_bf16_f32 v2, v8, v12
	s_mul_i32 s4, s4, 0x480000
	ds_write_b32 v167, v2 offset:160
	v_cvt_pk_bf16_f32 v2, v9, v13
	v_lshl_add_u64 v[10:11], v[158:159], 0, s[4:5]
	ds_write_b32 v167, v2 offset:240
	v_add_co_u32_e32 v2, vcc, s73, v10
	s_min_u32 s4, s18, 28
	s_nop 0
	v_addc_co_u32_e32 v3, vcc, 0, v11, vcc
	v_add_co_u32_e32 v6, vcc, s74, v10
	global_load_dwordx4 v[2:5], v[2:3], off nt
	s_nop 0
	v_addc_co_u32_e32 v7, vcc, 0, v11, vcc
	global_load_dwordx4 v[14:17], v[6:7], off nt
	v_add_co_u32_e32 v6, vcc, s75, v10
	s_mulk_i32 s4, 0x2400
	s_nop 0
	v_addc_co_u32_e32 v7, vcc, 0, v11, vcc
	v_add_co_u32_e32 v10, vcc, s84, v10
	global_load_dwordx4 v[6:9], v[6:7], off nt
	s_nop 0
	v_addc_co_u32_e32 v11, vcc, 0, v11, vcc
	global_load_dwordx4 v[10:13], v[10:11], off nt
	ds_read_b128 v[172:175], v168
	ds_read_b128 v[176:179], v168 offset:1280
	ds_read_b128 v[180:183], v169 offset:20480
	ds_read_b128 v[184:187], v169 offset:21504
	ds_read_b128 v[188:191], v169 offset:22528
	ds_read_b128 v[196:199], v169 offset:23552
	ds_read_b128 v[200:203], v169 offset:24576
	ds_read_b128 v[204:207], v169 offset:25600
	ds_read_b128 v[208:211], v169 offset:26624
	ds_read_b128 v[212:215], v169 offset:27648
	ds_read_b128 v[216:219], v169 offset:28672
	s_waitcnt lgkmcnt(8)
	v_mfma_f32_16x16x32_bf16 v[118:121], v[180:183], v[172:175], v[118:121]
	s_add_u32 s4, s14, s4
	s_addc_u32 s21, s15, 0
	s_add_u32 s20, s4, 0x6c00
	v_mfma_f32_16x16x32_bf16 v[90:93], v[180:183], v[176:179], v[90:93]
	s_addc_u32 s21, s21, 0
	s_add_i32 s19, s19, 3
	s_min_u32 s4, s19, 29
	s_waitcnt lgkmcnt(7)
	v_mfma_f32_16x16x32_bf16 v[114:117], v[184:187], v[172:175], v[114:117]
	s_mul_i32 s4, s4, 0x480000
	v_mfma_f32_16x16x32_bf16 v[78:81], v[184:187], v[176:179], v[78:81]
	s_waitcnt lgkmcnt(6)
	v_mfma_f32_16x16x32_bf16 v[110:113], v[188:191], v[172:175], v[110:113]
	v_mfma_f32_16x16x32_bf16 v[74:77], v[188:191], v[176:179], v[74:77]
	s_waitcnt lgkmcnt(5)
	v_mfma_f32_16x16x32_bf16 v[106:109], v[196:199], v[172:175], v[106:109]
	v_mfma_f32_16x16x32_bf16 v[70:73], v[196:199], v[176:179], v[70:73]
	s_waitcnt lgkmcnt(4)
	v_mfma_f32_16x16x32_bf16 v[102:105], v[200:203], v[172:175], v[102:105]
	v_mfma_f32_16x16x32_bf16 v[66:69], v[200:203], v[176:179], v[66:69]
	s_waitcnt lgkmcnt(3)
	v_mfma_f32_16x16x32_bf16 v[98:101], v[204:207], v[172:175], v[98:101]
	v_mfma_f32_16x16x32_bf16 v[62:65], v[204:207], v[176:179], v[62:65]
	s_waitcnt vmcnt(7)
	ds_write_b128 v170, v[38:41] offset:29696
	s_waitcnt vmcnt(6)
	ds_write_b128 v171, v[42:45] offset:37888
	v_lshl_add_u64 v[38:39], s[20:21], 0, v[164:165]
	v_lshl_add_u64 v[42:43], s[20:21], 0, v[124:125]
	global_load_dwordx4 v[38:41], v[38:39], off
	s_waitcnt lgkmcnt(4)
	v_mfma_f32_16x16x32_bf16 v[94:97], v[208:211], v[172:175], v[94:97]
	global_load_dwordx4 v[42:45], v[42:43], off
	s_waitcnt lgkmcnt(0)
	s_barrier
	v_cvt_pk_bf16_f32 v26, v26, v30
	ds_write_b32 v166, v26
	v_cvt_pk_bf16_f32 v26, v27, v31
	ds_write_b32 v166, v26 offset:80
	v_cvt_pk_bf16_f32 v26, v28, v32
	ds_write_b32 v166, v26 offset:160
	v_cvt_pk_bf16_f32 v26, v29, v33
	ds_write_b32 v166, v26 offset:240
	v_cvt_pk_bf16_f32 v26, v34, v50
	ds_write_b32 v167, v26
	v_cvt_pk_bf16_f32 v26, v35, v51
	ds_write_b32 v167, v26 offset:80
	v_cvt_pk_bf16_f32 v26, v36, v52
	ds_write_b32 v167, v26 offset:160
	v_cvt_pk_bf16_f32 v26, v37, v53
	v_lshl_add_u64 v[50:51], v[158:159], 0, s[4:5]
	ds_write_b32 v167, v26 offset:240
	v_add_co_u32_e32 v26, vcc, s73, v50
	v_mfma_f32_16x16x32_bf16 v[58:61], v[208:211], v[176:179], v[58:61]
	s_nop 0
	v_addc_co_u32_e32 v27, vcc, 0, v51, vcc
	v_add_co_u32_e32 v30, vcc, s74, v50
	global_load_dwordx4 v[26:29], v[26:27], off nt
	s_nop 0
	v_addc_co_u32_e32 v31, vcc, 0, v51, vcc
	v_add_co_u32_e32 v34, vcc, s75, v50
	global_load_dwordx4 v[30:33], v[30:31], off nt
	s_nop 0
	v_addc_co_u32_e32 v35, vcc, 0, v51, vcc
	v_add_co_u32_e32 v50, vcc, s84, v50
	global_load_dwordx4 v[34:37], v[34:35], off nt
	s_nop 0
	v_addc_co_u32_e32 v51, vcc, 0, v51, vcc
	global_load_dwordx4 v[50:53], v[50:51], off nt
	v_mfma_f32_16x16x32_bf16 v[86:89], v[212:215], v[172:175], v[86:89]
	s_min_u32 s4, s19, 28
	s_mulk_i32 s4, 0x2400
	s_add_u32 s4, s14, s4
	v_mfma_f32_16x16x32_bf16 v[54:57], v[212:215], v[176:179], v[54:57]
	s_addc_u32 s19, s15, 0
	s_add_u32 s20, s4, 0x6c00
	s_addc_u32 s21, s19, 0
	v_mfma_f32_16x16x32_bf16 v[82:85], v[216:219], v[172:175], v[82:85]
	s_cmp_lt_u32 s18, 30
	s_mov_b32 s19, s18
	v_mfma_f32_16x16x32_bf16 v[46:49], v[216:219], v[176:179], v[46:49]
	ds_read_b128 v[172:175], v168
	ds_read_b128 v[176:179], v168 offset:1280
	ds_read_b128 v[180:183], v169 offset:29696
	ds_read_b128 v[184:187], v169 offset:30720
	ds_read_b128 v[188:191], v169 offset:31744
	ds_read_b128 v[196:199], v169 offset:32768
	ds_read_b128 v[200:203], v169 offset:33792
	ds_read_b128 v[204:207], v169 offset:34816
	ds_read_b128 v[208:211], v169 offset:35840
	ds_read_b128 v[212:215], v169 offset:36864
	ds_read_b128 v[216:219], v169 offset:37888
	s_waitcnt lgkmcnt(8)
	v_mfma_f32_16x16x32_bf16 v[118:121], v[180:183], v[172:175], v[118:121]
	v_mfma_f32_16x16x32_bf16 v[90:93], v[180:183], v[176:179], v[90:93]
	s_waitcnt lgkmcnt(7)
	v_mfma_f32_16x16x32_bf16 v[114:117], v[184:187], v[172:175], v[114:117]
	v_mfma_f32_16x16x32_bf16 v[78:81], v[184:187], v[176:179], v[78:81]
	s_waitcnt lgkmcnt(6)
	v_mfma_f32_16x16x32_bf16 v[110:113], v[188:191], v[172:175], v[110:113]
	v_mfma_f32_16x16x32_bf16 v[74:77], v[188:191], v[176:179], v[74:77]
	s_waitcnt lgkmcnt(5)
	v_mfma_f32_16x16x32_bf16 v[106:109], v[196:199], v[172:175], v[106:109]
	v_mfma_f32_16x16x32_bf16 v[70:73], v[196:199], v[176:179], v[70:73]
	s_waitcnt lgkmcnt(4)
	v_mfma_f32_16x16x32_bf16 v[102:105], v[200:203], v[172:175], v[102:105]
	v_mfma_f32_16x16x32_bf16 v[66:69], v[200:203], v[176:179], v[66:69]
	s_waitcnt lgkmcnt(3)
	v_mfma_f32_16x16x32_bf16 v[98:101], v[204:207], v[172:175], v[98:101]
	v_mfma_f32_16x16x32_bf16 v[62:65], v[204:207], v[176:179], v[62:65]
	s_waitcnt vmcnt(11)
	ds_write_b128 v170, v[18:21] offset:20480
	s_waitcnt vmcnt(10)
	ds_write_b128 v171, v[22:25] offset:28672
	v_lshl_add_u64 v[18:19], s[20:21], 0, v[164:165]
	v_lshl_add_u64 v[22:23], s[20:21], 0, v[124:125]
	global_load_dwordx4 v[18:21], v[18:19], off
	s_waitcnt lgkmcnt(4)
	v_mfma_f32_16x16x32_bf16 v[94:97], v[208:211], v[172:175], v[94:97]
	global_load_dwordx4 v[22:25], v[22:23], off
	s_waitcnt lgkmcnt(0)
	s_barrier
; #define LAS __attribute__((address_space(3)))
; #define MODI_ALOAD(r, s) do { const int s_ = (s) < nsteps ? (s) : nsteps - 1; ar[r][0] = *(const GAS v4u*)(Cb + (size_t)s_ * 9216 + c1); ar[r][1] = *(const GAS v4u*)(Cb + (size_t)s_ * 9216 + c2); } while (0)
; #define MODI_AWRITE(r, s) do { *(LAS v4u*)(la + ((s) & 1) * MODI_A_BYTES + c1) = ar[r][0]; *(LAS v4u*)(la + ((s) & 1) * MODI_A_BYTES + c2) = ar[r][1]; } while (0)
; __device__ __forceinline__ void mod_item256(Frame& F, const Args& A, int cg, int k0, int nsteps, float* dst, int ldd, int dcol0, const float* bias) {
;     ...
;             for (int mg = 0; mg < 3; ++mg) { bf16x8 af[3];
; #pragma unroll
;                 for (int i = 0; i < 3; ++i) af[i] = *(const LAS bf16x8*)(la + (s & 1) * MODI_A_BYTES + (3 * mg + i) * 1024 + lane * 16);
; #pragma unroll
;                 for (int i = 0; i < 3; ++i)
; #pragma unroll
;                     for (int j = 0; j < 2; ++j) acc[3 * mg + i][j] = __builtin_amdgcn_mfma_f32_16x16x32_bf16(af[i], bfr[j], acc[3 * mg + i][j], 0, 0, 0);
;                 asm volatile("" ::: "memory"); }
;             MODI_AWRITE((b + 1) & 1, s + 1);
;             asm volatile("" ::: "memory");
;             MODI_ALOAD((b + 1) & 1, s + 3);
;             __syncthreads();
;         }
;     }
;     ...
;     const int c0 = 32 * w + (lane & 15);
; #pragma unroll
;     for (int j = 0; j < 2; ++j) { const float bv = bias ? bias[256 * cg + c0 + 16 * j] : 0.f;
; #pragma unroll
;         for (int mt = 0; mt < 9; ++mt)
; #pragma unroll
;             for (int r = 0; r < 4; ++r) { const int row = 16 * mt + 4 * (lane >> 4) + r;
;                 if (row <= DBATCH) dst[(size_t)row * ldd + dcol0 + c0 + 16 * j] = acc[mt][j][r] + bv; } }
	v_mfma_f32_16x16x32_bf16 v[58:61], v[208:211], v[176:179], v[58:61]
	v_mfma_f32_16x16x32_bf16 v[86:89], v[212:215], v[172:175], v[86:89]
	v_mfma_f32_16x16x32_bf16 v[54:57], v[212:215], v[176:179], v[54:57]
	v_mfma_f32_16x16x32_bf16 v[82:85], v[216:219], v[172:175], v[82:85]
	v_mfma_f32_16x16x32_bf16 v[46:49], v[216:219], v[176:179], v[46:49]
	s_cbranch_scc1 .LBB0_354
	s_mul_i32 s17, s17, 0x60c000
	s_add_u32 s4, s8, s17
	s_addc_u32 s18, s9, 0
	s_lshl_b32 s14, s16, 8
	s_ashr_i32 s15, s14, 31
	s_lshl_b64 s[16:17], s[14:15], 2
	s_add_u32 s16, s4, s16
	s_addc_u32 s17, s18, s17
	s_waitcnt vmcnt(9)
	v_lshl_add_u64 v[6:7], v[126:127], 2, s[16:17]
	v_add_f32_e32 v4, 0, v118
	v_lshl_add_u64 v[2:3], v[6:7], 0, v[128:129]
	global_store_dword v[2:3], v4, off
	v_add_f32_e32 v8, 0, v119
	v_lshl_add_u64 v[4:5], v[6:7], 0, v[130:131]
	s_mov_b32 s4, 0x18000
	global_store_dword v[4:5], v8, off
	v_add_co_u32_e32 v4, vcc, s4, v2
	v_add_f32_e32 v8, 0, v120
	s_nop 0
	v_addc_co_u32_e32 v5, vcc, 0, v3, vcc
	global_store_dword v[4:5], v8, off
	v_add_f32_e32 v4, 0, v121
	s_waitcnt vmcnt(3)
	v_lshl_add_u64 v[24:25], v[6:7], 0, v[132:133]
	s_mov_b32 s4, 0xc0000
	global_store_dword v[24:25], v4, off
	v_add_co_u32_e32 v4, vcc, s4, v2
	v_add_f32_e32 v8, 0, v114
	s_nop 0
	v_addc_co_u32_e32 v5, vcc, 0, v3, vcc
	s_mov_b32 s4, 0xcc000
	global_store_dword v[4:5], v8, off
	v_add_co_u32_e32 v4, vcc, s4, v2
	v_add_f32_e32 v8, 0, v115
	s_nop 0
	v_addc_co_u32_e32 v5, vcc, 0, v3, vcc
	s_mov_b32 s4, 0xd8000
	global_store_dword v[4:5], v8, off
	v_add_co_u32_e32 v4, vcc, s4, v2
	v_add_f32_e32 v8, 0, v116
	s_nop 0
	v_addc_co_u32_e32 v5, vcc, 0, v3, vcc
	global_store_dword v[4:5], v8, off
	v_add_f32_e32 v4, 0, v117
	v_lshl_add_u64 v[22:23], v[6:7], 0, v[134:135]
	s_mov_b32 s4, 0x180000
	global_store_dword v[22:23], v4, off
	v_add_co_u32_e32 v4, vcc, s4, v2
	v_add_f32_e32 v8, 0, v110
	s_nop 0
	v_addc_co_u32_e32 v5, vcc, 0, v3, vcc
	s_mov_b32 s4, 0x18c000
	global_store_dword v[4:5], v8, off
	v_add_co_u32_e32 v4, vcc, s4, v2
	v_add_f32_e32 v8, 0, v111
	s_nop 0
	v_addc_co_u32_e32 v5, vcc, 0, v3, vcc
	s_mov_b32 s4, 0x198000
	global_store_dword v[4:5], v8, off
	v_add_co_u32_e32 v4, vcc, s4, v2
	v_add_f32_e32 v8, 0, v112
	s_nop 0
	v_addc_co_u32_e32 v5, vcc, 0, v3, vcc
	global_store_dword v[4:5], v8, off
	v_add_f32_e32 v4, 0, v113
	v_lshl_add_u64 v[18:19], v[6:7], 0, v[136:137]
	v_add_co_u32_e32 v20, vcc, s55, v2
	global_store_dword v[18:19], v4, off
	v_add_f32_e32 v4, 0, v106
	v_addc_co_u32_e32 v21, vcc, 0, v3, vcc
	s_mov_b32 s4, 0x24c000
	global_store_dword v[20:21], v4, off
	v_add_co_u32_e32 v4, vcc, s4, v2
	v_add_f32_e32 v8, 0, v107
	s_nop 0
	v_addc_co_u32_e32 v5, vcc, 0, v3, vcc
	s_mov_b32 s4, 0x258000
	global_store_dword v[4:5], v8, off
	v_add_co_u32_e32 v4, vcc, s4, v2
	v_add_f32_e32 v8, 0, v108
	s_nop 0
	v_addc_co_u32_e32 v5, vcc, 0, v3, vcc
	global_store_dword v[4:5], v8, off
	v_add_f32_e32 v4, 0, v109
	v_lshl_add_u64 v[16:17], v[6:7], 0, v[138:139]
	global_store_dword v[16:17], v4, off
	v_add_f32_e32 v8, 0, v102
	v_lshl_add_u64 v[4:5], v[6:7], 0, v[140:141]
	global_store_dword v[4:5], v8, off
	v_add_f32_e32 v8, 0, v103
	v_lshl_add_u64 v[4:5], v[6:7], 0, v[142:143]
	s_mov_b32 s4, 0x318000
	global_store_dword v[4:5], v8, off
	v_add_co_u32_e32 v4, vcc, s4, v2
	v_add_f32_e32 v8, 0, v104
	s_nop 0
	v_addc_co_u32_e32 v5, vcc, 0, v3, vcc
	global_store_dword v[4:5], v8, off
	v_add_f32_e32 v4, 0, v105
	v_lshl_add_u64 v[14:15], v[6:7], 0, v[144:145]
	s_mov_b32 s4, 0x3c0000
	global_store_dword v[14:15], v4, off
	v_add_co_u32_e32 v4, vcc, s4, v2
	v_add_f32_e32 v8, 0, v98
	s_nop 0
	v_addc_co_u32_e32 v5, vcc, 0, v3, vcc
	s_mov_b32 s4, 0x3cc000
	global_store_dword v[4:5], v8, off
	v_add_co_u32_e32 v4, vcc, s4, v2
	v_add_f32_e32 v8, 0, v99
	s_nop 0
	v_addc_co_u32_e32 v5, vcc, 0, v3, vcc
	s_mov_b32 s4, 0x3d8000
	global_store_dword v[4:5], v8, off
	v_add_co_u32_e32 v4, vcc, s4, v2
	v_add_f32_e32 v8, 0, v100
	s_nop 0
	v_addc_co_u32_e32 v5, vcc, 0, v3, vcc
	global_store_dword v[4:5], v8, off
	v_add_f32_e32 v4, 0, v101
	v_lshl_add_u64 v[10:11], v[6:7], 0, v[146:147]
	v_add_co_u32_e32 v12, vcc, s72, v2
	global_store_dword v[10:11], v4, off
	v_add_f32_e32 v4, 0, v94
	v_addc_co_u32_e32 v13, vcc, 0, v3, vcc
	s_mov_b32 s4, 0x48c000
	global_store_dword v[12:13], v4, off
	v_add_co_u32_e32 v4, vcc, s4, v2
	v_add_f32_e32 v8, 0, v95
	s_nop 0
	v_addc_co_u32_e32 v5, vcc, 0, v3, vcc
	s_mov_b32 s4, 0x498000
	global_store_dword v[4:5], v8, off
	v_add_co_u32_e32 v4, vcc, s4, v2
	v_add_f32_e32 v8, 0, v96
	s_nop 0
	v_addc_co_u32_e32 v5, vcc, 0, v3, vcc
	global_store_dword v[4:5], v8, off
	v_add_f32_e32 v4, 0, v97
	v_lshl_add_u64 v[8:9], v[6:7], 0, v[148:149]
	s_mov_b32 s4, 0x540000
	global_store_dword v[8:9], v4, off
	v_add_co_u32_e32 v4, vcc, s4, v2
	v_add_f32_e32 v26, 0, v86
	s_nop 0
	v_addc_co_u32_e32 v5, vcc, 0, v3, vcc
	global_store_dword v[4:5], v26, off
	v_add_co_u32_e32 v4, vcc, 0x54c000, v2
	v_add_f32_e32 v26, 0, v87
	s_nop 0
	v_addc_co_u32_e32 v5, vcc, 0, v3, vcc
	global_store_dword v[4:5], v26, off
	v_add_co_u32_e32 v4, vcc, 0x558000, v2
	v_add_f32_e32 v26, 0, v88
	s_nop 0
	v_addc_co_u32_e32 v5, vcc, 0, v3, vcc
	global_store_dword v[4:5], v26, off
	v_add_f32_e32 v26, 0, v89
	v_lshl_add_u64 v[4:5], v[6:7], 0, v[150:151]
	global_store_dword v[4:5], v26, off
	s_and_saveexec_b64 s[16:17], s[2:3]
	s_cbranch_execz .LBB0_357
	v_add_f32_e32 v28, 0, v82
	v_lshl_add_u64 v[26:27], v[6:7], 0, v[152:153]
	global_store_dword v[26:27], v28, off

; __device__ __forceinline__ unsigned cvt_pk_bf16(float lo, float hi) { unsigned r; asm volatile("v_cvt_pk_bf16_f32 %0, %1, %2" : "=v"(r) : "v"(lo), "v"(hi)); return r; }
; #define LAS __attribute__((address_space(3)))
; #define MODI_LOAD(b, s) do { _Pragma("unroll") for (int i = 0; i < 4; ++i) buf[b][i] = __builtin_nontemporal_load((const GAS f32x4*)(Wb + (size_t)(32 * (s) + 16 * (i >> 1) + (i & 1)) * (MODW * 4) + wlo)); } while (0)
; #define MODI_ALOAD(r, s) do { const int s_ = (s) < nsteps ? (s) : nsteps - 1; ar[r][0] = *(const GAS v4u*)(Cb + (size_t)s_ * 9216 + c1); ar[r][1] = *(const GAS v4u*)(Cb + (size_t)s_ * 9216 + c2); } while (0)
; __device__ __forceinline__ void mod_item256(Frame& F, const Args& A, int cg, int k0, int nsteps, float* dst, int ldd, int dcol0, const float* bias) {
;     ...
;     for (int s4 = 0; s4 < nsteps; s4 += 2) {
; #pragma unroll
;         for (int b = 0; b < 2; ++b) { const int s = s4 + b;
; #pragma unroll
;             for (int ip = 0; ip < 2; ++ip)
; #pragma unroll
;                 for (int e = 0; e < 4; ++e) { const int n = n4 + e, k = 2 * kp + 16 * ip;
;                     *(LAS unsigned*)(sb + n * 80 + (((k >> 3) ^ (a8 & 3)) * 16) + (k & 7) * 2) = pg8::cvt_pk_bf16(buf[b][2 * ip][e], buf[b][2 * ip + 1][e]); }
;             asm volatile("" ::: "memory");
;             { const int sn = (s + 2 < nsteps) ? s + 2 : nsteps - 1; MODI_LOAD(b, sn); }
;             asm volatile("" ::: "memory");
;             bf16x8 bfr[2];
; #pragma unroll
;             for (int j = 0; j < 2; ++j) { const int n = 16 * j + (lane & 15); bfr[j] = *(const LAS bf16x8*)(sb + n * 80 + (((lane >> 4) ^ ((n >> 2) & 3)) * 16)); }
; #pragma unroll
;             for (int mg = 0; mg < 3; ++mg) { bf16x8 af[3];
; #pragma unroll
;                 for (int i = 0; i < 3; ++i) af[i] = *(const LAS bf16x8*)(la + (s & 1) * MODI_A_BYTES + (3 * mg + i) * 1024 + lane * 16);
; #pragma unroll
;                 for (int i = 0; i < 3; ++i)
; #pragma unroll
;                     for (int j = 0; j < 2; ++j) acc[3 * mg + i][j] = __builtin_amdgcn_mfma_f32_16x16x32_bf16(af[i], bfr[j], acc[3 * mg + i][j], 0, 0, 0);
;                 asm volatile("" ::: "memory"); }
;             MODI_AWRITE((b + 1) & 1, s + 1);
;             asm volatile("" ::: "memory");
;             MODI_ALOAD((b + 1) & 1, s + 3);
;             __syncthreads();
;         }
;     }
.LBB0_533:
	s_waitcnt vmcnt(10)
	v_cvt_pk_bf16_f32 v2, v2, v14
	ds_write_b32 v167, v2
	v_cvt_pk_bf16_f32 v2, v3, v15
	ds_write_b32 v167, v2 offset:80
	v_cvt_pk_bf16_f32 v2, v4, v16
	ds_write_b32 v167, v2 offset:160
	v_cvt_pk_bf16_f32 v2, v5, v17
	s_add_i32 s18, s19, 2
	ds_write_b32 v167, v2 offset:240
	s_waitcnt vmcnt(8)
	v_cvt_pk_bf16_f32 v2, v6, v10
	ds_write_b32 v168, v2
	v_cvt_pk_bf16_f32 v2, v7, v11
	s_min_u32 s6, s18, 29
	ds_write_b32 v168, v2 offset:80
	v_cvt_pk_bf16_f32 v2, v8, v12
	s_mul_i32 s6, s6, 0x480000
	ds_write_b32 v168, v2 offset:160
	v_cvt_pk_bf16_f32 v2, v9, v13
	v_lshl_add_u64 v[10:11], v[158:159], 0, s[6:7]
	ds_write_b32 v168, v2 offset:240
	v_add_co_u32_e32 v2, vcc, s75, v10
	s_min_u32 s6, s18, 28
	s_nop 0
	v_addc_co_u32_e32 v3, vcc, 0, v11, vcc
	v_add_co_u32_e32 v6, vcc, s76, v10
	global_load_dwordx4 v[2:5], v[2:3], off nt
	s_nop 0
	v_addc_co_u32_e32 v7, vcc, 0, v11, vcc
	global_load_dwordx4 v[14:17], v[6:7], off nt
	v_add_co_u32_e32 v6, vcc, s77, v10
	s_mulk_i32 s6, 0x2400
	s_nop 0
	v_addc_co_u32_e32 v7, vcc, 0, v11, vcc
	v_add_co_u32_e32 v10, vcc, s78, v10
	global_load_dwordx4 v[6:9], v[6:7], off nt
	s_nop 0
	v_addc_co_u32_e32 v11, vcc, 0, v11, vcc
	global_load_dwordx4 v[10:13], v[10:11], off nt
	ds_read_b128 v[174:177], v169
	ds_read_b128 v[178:181], v169 offset:1280
	ds_read_b128 v[182:185], v170 offset:20480
	ds_read_b128 v[186:189], v170 offset:21504
	ds_read_b128 v[190:193], v170 offset:22528
	ds_read_b128 v[196:199], v170 offset:23552
	ds_read_b128 v[200:203], v170 offset:24576
	ds_read_b128 v[204:207], v170 offset:25600
	ds_read_b128 v[208:211], v170 offset:26624
	ds_read_b128 v[212:215], v170 offset:27648
	ds_read_b128 v[216:219], v170 offset:28672
	s_waitcnt lgkmcnt(8)
	v_mfma_f32_16x16x32_bf16 v[118:121], v[182:185], v[174:177], v[118:121]
	s_add_u32 s6, s14, s6
	s_addc_u32 s21, s15, 0
	s_add_u32 s20, s6, 0x6c00
	v_mfma_f32_16x16x32_bf16 v[90:93], v[182:185], v[178:181], v[90:93]
	s_addc_u32 s21, s21, 0
	s_add_i32 s19, s19, 3
	s_min_u32 s6, s19, 29
	s_waitcnt lgkmcnt(7)
	v_mfma_f32_16x16x32_bf16 v[114:117], v[186:189], v[174:177], v[114:117]
	s_mul_i32 s6, s6, 0x480000
	v_mfma_f32_16x16x32_bf16 v[78:81], v[186:189], v[178:181], v[78:81]
	s_waitcnt lgkmcnt(6)
	v_mfma_f32_16x16x32_bf16 v[110:113], v[190:193], v[174:177], v[110:113]
	v_mfma_f32_16x16x32_bf16 v[74:77], v[190:193], v[178:181], v[74:77]
	s_waitcnt lgkmcnt(5)
	v_mfma_f32_16x16x32_bf16 v[106:109], v[196:199], v[174:177], v[106:109]
	v_mfma_f32_16x16x32_bf16 v[70:73], v[196:199], v[178:181], v[70:73]
	s_waitcnt lgkmcnt(4)
	v_mfma_f32_16x16x32_bf16 v[102:105], v[200:203], v[174:177], v[102:105]
	v_mfma_f32_16x16x32_bf16 v[66:69], v[200:203], v[178:181], v[66:69]
	s_waitcnt lgkmcnt(3)
	v_mfma_f32_16x16x32_bf16 v[98:101], v[204:207], v[174:177], v[98:101]
	v_mfma_f32_16x16x32_bf16 v[62:65], v[204:207], v[178:181], v[62:65]
	s_waitcnt vmcnt(7)
	ds_write_b128 v171, v[38:41] offset:29696
	s_waitcnt vmcnt(6)
	ds_write_b128 v172, v[42:45] offset:37888
	v_lshl_add_u64 v[38:39], s[20:21], 0, v[164:165]
	v_lshl_add_u64 v[42:43], s[20:21], 0, v[124:125]
	global_load_dwordx4 v[38:41], v[38:39], off
	s_waitcnt lgkmcnt(4)
	v_mfma_f32_16x16x32_bf16 v[94:97], v[208:211], v[174:177], v[94:97]
	global_load_dwordx4 v[42:45], v[42:43], off
	s_waitcnt lgkmcnt(0)
	s_barrier
	v_cvt_pk_bf16_f32 v26, v26, v30
	ds_write_b32 v167, v26
	v_cvt_pk_bf16_f32 v26, v27, v31
	ds_write_b32 v167, v26 offset:80
	v_cvt_pk_bf16_f32 v26, v28, v32
	ds_write_b32 v167, v26 offset:160
	v_cvt_pk_bf16_f32 v26, v29, v33
	ds_write_b32 v167, v26 offset:240
	v_cvt_pk_bf16_f32 v26, v34, v50
	ds_write_b32 v168, v26
	v_cvt_pk_bf16_f32 v26, v35, v51
	ds_write_b32 v168, v26 offset:80
	v_cvt_pk_bf16_f32 v26, v36, v52
	ds_write_b32 v168, v26 offset:160
	v_cvt_pk_bf16_f32 v26, v37, v53
	v_lshl_add_u64 v[50:51], v[158:159], 0, s[6:7]
	ds_write_b32 v168, v26 offset:240
	v_add_co_u32_e32 v26, vcc, s75, v50
	v_mfma_f32_16x16x32_bf16 v[58:61], v[208:211], v[178:181], v[58:61]
	s_nop 0
	v_addc_co_u32_e32 v27, vcc, 0, v51, vcc
	v_add_co_u32_e32 v30, vcc, s76, v50
	global_load_dwordx4 v[26:29], v[26:27], off nt
	s_nop 0
	v_addc_co_u32_e32 v31, vcc, 0, v51, vcc
	v_add_co_u32_e32 v34, vcc, s77, v50
	global_load_dwordx4 v[30:33], v[30:31], off nt
	s_nop 0
	v_addc_co_u32_e32 v35, vcc, 0, v51, vcc
	v_add_co_u32_e32 v50, vcc, s78, v50
	global_load_dwordx4 v[34:37], v[34:35], off nt
	s_nop 0
	v_addc_co_u32_e32 v51, vcc, 0, v51, vcc
	global_load_dwordx4 v[50:53], v[50:51], off nt
	v_mfma_f32_16x16x32_bf16 v[86:89], v[212:215], v[174:177], v[86:89]
	s_min_u32 s6, s19, 28
	s_mulk_i32 s6, 0x2400
	s_add_u32 s6, s14, s6
	v_mfma_f32_16x16x32_bf16 v[54:57], v[212:215], v[178:181], v[54:57]
	s_addc_u32 s19, s15, 0
	s_add_u32 s20, s6, 0x6c00
	s_addc_u32 s21, s19, 0
	v_mfma_f32_16x16x32_bf16 v[82:85], v[216:219], v[174:177], v[82:85]
	s_cmp_lt_u32 s18, 30
	s_mov_b32 s19, s18
	v_mfma_f32_16x16x32_bf16 v[46:49], v[216:219], v[178:181], v[46:49]
	ds_read_b128 v[174:177], v169
	ds_read_b128 v[178:181], v169 offset:1280
	ds_read_b128 v[182:185], v170 offset:29696
	ds_read_b128 v[186:189], v170 offset:30720
	ds_read_b128 v[190:193], v170 offset:31744
	ds_read_b128 v[196:199], v170 offset:32768
	ds_read_b128 v[200:203], v170 offset:33792
	ds_read_b128 v[204:207], v170 offset:34816
	ds_read_b128 v[208:211], v170 offset:35840
	ds_read_b128 v[212:215], v170 offset:36864
	ds_read_b128 v[216:219], v170 offset:37888
	s_waitcnt lgkmcnt(8)
	v_mfma_f32_16x16x32_bf16 v[118:121], v[182:185], v[174:177], v[118:121]
	v_mfma_f32_16x16x32_bf16 v[90:93], v[182:185], v[178:181], v[90:93]
	s_waitcnt lgkmcnt(7)
	v_mfma_f32_16x16x32_bf16 v[114:117], v[186:189], v[174:177], v[114:117]
	v_mfma_f32_16x16x32_bf16 v[78:81], v[186:189], v[178:181], v[78:81]
	s_waitcnt lgkmcnt(6)
	v_mfma_f32_16x16x32_bf16 v[110:113], v[190:193], v[174:177], v[110:113]
	v_mfma_f32_16x16x32_bf16 v[74:77], v[190:193], v[178:181], v[74:77]
	s_waitcnt lgkmcnt(5)
	v_mfma_f32_16x16x32_bf16 v[106:109], v[196:199], v[174:177], v[106:109]
	v_mfma_f32_16x16x32_bf16 v[70:73], v[196:199], v[178:181], v[70:73]
	s_waitcnt lgkmcnt(4)
	v_mfma_f32_16x16x32_bf16 v[102:105], v[200:203], v[174:177], v[102:105]
	v_mfma_f32_16x16x32_bf16 v[66:69], v[200:203], v[178:181], v[66:69]
	s_waitcnt lgkmcnt(3)
	v_mfma_f32_16x16x32_bf16 v[98:101], v[204:207], v[174:177], v[98:101]
	v_mfma_f32_16x16x32_bf16 v[62:65], v[204:207], v[178:181], v[62:65]
	s_waitcnt vmcnt(11)
	ds_write_b128 v171, v[18:21] offset:20480
	s_waitcnt vmcnt(10)
	ds_write_b128 v172, v[22:25] offset:28672
	v_lshl_add_u64 v[18:19], s[20:21], 0, v[164:165]
	v_lshl_add_u64 v[22:23], s[20:21], 0, v[124:125]
	global_load_dwordx4 v[18:21], v[18:19], off
	s_waitcnt lgkmcnt(4)
	v_mfma_f32_16x16x32_bf16 v[94:97], v[208:211], v[174:177], v[94:97]
	global_load_dwordx4 v[22:25], v[22:23], off
	s_waitcnt lgkmcnt(0)
	s_barrier
; #define LAS __attribute__((address_space(3)))
; #define MODI_ALOAD(r, s) do { const int s_ = (s) < nsteps ? (s) : nsteps - 1; ar[r][0] = *(const GAS v4u*)(Cb + (size_t)s_ * 9216 + c1); ar[r][1] = *(const GAS v4u*)(Cb + (size_t)s_ * 9216 + c2); } while (0)
; #define MODI_AWRITE(r, s) do { *(LAS v4u*)(la + ((s) & 1) * MODI_A_BYTES + c1) = ar[r][0]; *(LAS v4u*)(la + ((s) & 1) * MODI_A_BYTES + c2) = ar[r][1]; } while (0)
; __device__ __forceinline__ void mod_item256(Frame& F, const Args& A, int cg, int k0, int nsteps, float* dst, int ldd, int dcol0, const float* bias) {
;     ...
;             for (int mg = 0; mg < 3; ++mg) { bf16x8 af[3];
; #pragma unroll
;                 for (int i = 0; i < 3; ++i) af[i] = *(const LAS bf16x8*)(la + (s & 1) * MODI_A_BYTES + (3 * mg + i) * 1024 + lane * 16);
; #pragma unroll
;                 for (int i = 0; i < 3; ++i)
; #pragma unroll
;                     for (int j = 0; j < 2; ++j) acc[3 * mg + i][j] = __builtin_amdgcn_mfma_f32_16x16x32_bf16(af[i], bfr[j], acc[3 * mg + i][j], 0, 0, 0);
;                 asm volatile("" ::: "memory"); }
;             MODI_AWRITE((b + 1) & 1, s + 1);
;             asm volatile("" ::: "memory");
;             MODI_ALOAD((b + 1) & 1, s + 3);
;             __syncthreads();
;         }
;     }
;     ...
;     const int c0 = 32 * w + (lane & 15);
; #pragma unroll
;     for (int j = 0; j < 2; ++j) { const float bv = bias ? bias[256 * cg + c0 + 16 * j] : 0.f;
; #pragma unroll
;         for (int mt = 0; mt < 9; ++mt)
; #pragma unroll
;             for (int r = 0; r < 4; ++r) { const int row = 16 * mt + 4 * (lane >> 4) + r;
;                 if (row <= DBATCH) dst[(size_t)row * ldd + dcol0 + c0 + 16 * j] = acc[mt][j][r] + bv; } }
	v_mfma_f32_16x16x32_bf16 v[58:61], v[208:211], v[178:181], v[58:61]
	v_mfma_f32_16x16x32_bf16 v[86:89], v[212:215], v[174:177], v[86:89]
	v_mfma_f32_16x16x32_bf16 v[54:57], v[212:215], v[178:181], v[54:57]
	v_mfma_f32_16x16x32_bf16 v[82:85], v[216:219], v[174:177], v[82:85]
	v_mfma_f32_16x16x32_bf16 v[46:49], v[216:219], v[178:181], v[46:49]
	s_cbranch_scc1 .LBB0_533
	s_mul_i32 s17, s17, 0x60c000
	s_add_u32 s6, s22, s17
	s_addc_u32 s18, s23, 0
	s_lshl_b32 s14, s16, 8
	s_ashr_i32 s15, s14, 31
	s_lshl_b64 s[16:17], s[14:15], 2
	s_add_u32 s16, s6, s16
	s_addc_u32 s17, s18, s17
	s_waitcnt vmcnt(9)
	v_lshl_add_u64 v[6:7], v[126:127], 2, s[16:17]
	v_add_f32_e32 v4, 0, v118
	v_lshl_add_u64 v[2:3], v[6:7], 0, v[128:129]
	global_store_dword v[2:3], v4, off
	v_add_f32_e32 v8, 0, v119
	v_lshl_add_u64 v[4:5], v[6:7], 0, v[130:131]
	s_mov_b32 s6, 0x18000
	global_store_dword v[4:5], v8, off
	v_add_co_u32_e32 v4, vcc, s6, v2
	v_add_f32_e32 v8, 0, v120
	s_nop 0
	v_addc_co_u32_e32 v5, vcc, 0, v3, vcc
	global_store_dword v[4:5], v8, off
	v_add_f32_e32 v4, 0, v121
	s_waitcnt vmcnt(3)
	v_lshl_add_u64 v[24:25], v[6:7], 0, v[132:133]
	s_mov_b32 s6, 0xc0000
	global_store_dword v[24:25], v4, off
	v_add_co_u32_e32 v4, vcc, s6, v2
	v_add_f32_e32 v8, 0, v114
	s_nop 0
	v_addc_co_u32_e32 v5, vcc, 0, v3, vcc
	s_mov_b32 s6, 0xcc000
	global_store_dword v[4:5], v8, off
	v_add_co_u32_e32 v4, vcc, s6, v2
	v_add_f32_e32 v8, 0, v115
	s_nop 0
	v_addc_co_u32_e32 v5, vcc, 0, v3, vcc
	s_mov_b32 s6, 0xd8000
	global_store_dword v[4:5], v8, off
	v_add_co_u32_e32 v4, vcc, s6, v2
	v_add_f32_e32 v8, 0, v116
	s_nop 0
	v_addc_co_u32_e32 v5, vcc, 0, v3, vcc
	global_store_dword v[4:5], v8, off
	v_add_f32_e32 v4, 0, v117
	v_lshl_add_u64 v[22:23], v[6:7], 0, v[134:135]
	s_mov_b32 s6, 0x180000
	global_store_dword v[22:23], v4, off
	v_add_co_u32_e32 v4, vcc, s6, v2
	v_add_f32_e32 v8, 0, v110
	s_nop 0
	v_addc_co_u32_e32 v5, vcc, 0, v3, vcc
	s_mov_b32 s6, 0x18c000
	global_store_dword v[4:5], v8, off
	v_add_co_u32_e32 v4, vcc, s6, v2
	v_add_f32_e32 v8, 0, v111
	s_nop 0
	v_addc_co_u32_e32 v5, vcc, 0, v3, vcc
	s_mov_b32 s6, 0x198000
	global_store_dword v[4:5], v8, off
	v_add_co_u32_e32 v4, vcc, s6, v2
	v_add_f32_e32 v8, 0, v112
	s_nop 0
	v_addc_co_u32_e32 v5, vcc, 0, v3, vcc
	global_store_dword v[4:5], v8, off
	v_add_f32_e32 v4, 0, v113
	v_lshl_add_u64 v[18:19], v[6:7], 0, v[136:137]
	v_add_co_u32_e32 v20, vcc, s59, v2
	global_store_dword v[18:19], v4, off
	v_add_f32_e32 v4, 0, v106
	v_addc_co_u32_e32 v21, vcc, 0, v3, vcc
	s_mov_b32 s6, 0x24c000
	global_store_dword v[20:21], v4, off
	v_add_co_u32_e32 v4, vcc, s6, v2
	v_add_f32_e32 v8, 0, v107
	s_nop 0
	v_addc_co_u32_e32 v5, vcc, 0, v3, vcc
	s_mov_b32 s6, 0x258000
	global_store_dword v[4:5], v8, off
	v_add_co_u32_e32 v4, vcc, s6, v2
	v_add_f32_e32 v8, 0, v108
	s_nop 0
	v_addc_co_u32_e32 v5, vcc, 0, v3, vcc
	global_store_dword v[4:5], v8, off
	v_add_f32_e32 v4, 0, v109
	v_lshl_add_u64 v[16:17], v[6:7], 0, v[138:139]
	global_store_dword v[16:17], v4, off
	v_add_f32_e32 v8, 0, v102
	v_lshl_add_u64 v[4:5], v[6:7], 0, v[140:141]
	global_store_dword v[4:5], v8, off
	v_add_f32_e32 v8, 0, v103
	v_lshl_add_u64 v[4:5], v[6:7], 0, v[142:143]
	s_mov_b32 s6, 0x318000
	global_store_dword v[4:5], v8, off
	v_add_co_u32_e32 v4, vcc, s6, v2
	v_add_f32_e32 v8, 0, v104
	s_nop 0
	v_addc_co_u32_e32 v5, vcc, 0, v3, vcc
	global_store_dword v[4:5], v8, off
	v_add_f32_e32 v4, 0, v105
	v_lshl_add_u64 v[14:15], v[6:7], 0, v[144:145]
	s_mov_b32 s6, 0x3c0000
	global_store_dword v[14:15], v4, off
	v_add_co_u32_e32 v4, vcc, s6, v2
	v_add_f32_e32 v8, 0, v98
	s_nop 0
	v_addc_co_u32_e32 v5, vcc, 0, v3, vcc
	s_mov_b32 s6, 0x3cc000
	global_store_dword v[4:5], v8, off
	v_add_co_u32_e32 v4, vcc, s6, v2
	v_add_f32_e32 v8, 0, v99
	s_nop 0
	v_addc_co_u32_e32 v5, vcc, 0, v3, vcc
	global_store_dword v[4:5], v8, off
	v_add_co_u32_e32 v4, vcc, s79, v2
	v_add_f32_e32 v8, 0, v100
	s_nop 0
	v_addc_co_u32_e32 v5, vcc, 0, v3, vcc
	global_store_dword v[4:5], v8, off
	v_add_f32_e32 v4, 0, v101
	v_lshl_add_u64 v[10:11], v[6:7], 0, v[146:147]
	v_add_co_u32_e32 v12, vcc, s74, v2
	global_store_dword v[10:11], v4, off
	v_add_f32_e32 v4, 0, v94
	v_addc_co_u32_e32 v13, vcc, 0, v3, vcc
	global_store_dword v[12:13], v4, off
	v_add_co_u32_e32 v4, vcc, s84, v2
	v_add_f32_e32 v8, 0, v95
	s_nop 0
	v_addc_co_u32_e32 v5, vcc, 0, v3, vcc
	global_store_dword v[4:5], v8, off
	v_add_co_u32_e32 v4, vcc, s85, v2
	v_add_f32_e32 v8, 0, v96
	s_nop 0
	v_addc_co_u32_e32 v5, vcc, 0, v3, vcc
	global_store_dword v[4:5], v8, off
	v_add_f32_e32 v4, 0, v97
	v_lshl_add_u64 v[8:9], v[6:7], 0, v[148:149]
	global_store_dword v[8:9], v4, off
	v_add_co_u32_e32 v4, vcc, s86, v2
	v_add_f32_e32 v26, 0, v86
	s_nop 0
	v_addc_co_u32_e32 v5, vcc, 0, v3, vcc
	global_store_dword v[4:5], v26, off
	v_add_co_u32_e32 v4, vcc, 0x54c000, v2
	v_add_f32_e32 v26, 0, v87
	s_nop 0
	v_addc_co_u32_e32 v5, vcc, 0, v3, vcc
	global_store_dword v[4:5], v26, off
	v_add_co_u32_e32 v4, vcc, 0x558000, v2
	v_add_f32_e32 v26, 0, v88
	s_nop 0
	v_addc_co_u32_e32 v5, vcc, 0, v3, vcc
	global_store_dword v[4:5], v26, off
	v_add_f32_e32 v26, 0, v89
	v_lshl_add_u64 v[4:5], v[6:7], 0, v[150:151]
	global_store_dword v[4:5], v26, off
	s_and_saveexec_b64 s[16:17], s[2:3]
	s_cbranch_execz .LBB0_536
	v_add_f32_e32 v28, 0, v82
	v_lshl_add_u64 v[26:27], v[6:7], 0, v[152:153]
	global_store_dword v[26:27], v28, off
